# GEMM K-loops: 22 LDS-DMA loads use the SGPR-base + 32-bit lane offset form, dropping one 64-bit VALU add each
# baseline (speedup 1.0000x reference)
; #define PG8_STAGE(bufoff, gbase, voff) do { _Pragma("unroll") for (int _i = 0; _i < 2; ++_i) \
;         __builtin_amdgcn_global_load_lds((const unsigned*)((const char*)(gbase) + (voff)[_i]), (LAS unsigned*)(lds + (bufoff) + ldsw + _i * 8192), 16, 0, 0); } while (0)
; #define PG8_LDA(dst, b, h) do { _Pragma("unroll") for (int m = 0; m < 4; ++m) _Pragma("unroll") for (int k = 0; k < 2; ++k) dst[m][k] = *(const LAS bf16x8*)(lds + PG8_SA(b, h) + aoff + m * 2048 + k * 1024); } while (0)
; #define PG8_LDB(dst, b, h) do { _Pragma("unroll") for (int n = 0; n < 2; ++n) _Pragma("unroll") for (int k = 0; k < 2; ++k) dst[n][k] = *(const LAS bf16x8*)(lds + PG8_SB(b, h) + boff + n * 2048 + k * 1024); } while (0)
; #define PG8_MMA(ai, bj, At, Bt_) do { __builtin_amdgcn_s_setprio(1); _Pragma("unroll") for (int m = 0; m < 4; ++m) _Pragma("unroll") for (int n = 0; n < 2; ++n) _Pragma("unroll") for (int k = 0; k < 2; ++k) \
;         acc[ai][bj][m][n] = __builtin_amdgcn_mfma_f32_16x16x32_bf16(Bt_[n][k], At[m][k], acc[ai][bj][m][n], 0, 0, 0); __builtin_amdgcn_s_setprio(0); } while (0)
; #define PG8_WAIT_L(n) asm volatile("s_waitcnt lgkmcnt(" #n ")" ::: "memory")
; #define PG8_BAR __builtin_amdgcn_s_barrier()
; #define PG8_SCHED __builtin_amdgcn_sched_barrier(0)
; template <bool REMAP>
; DI void gemm_phase(LAS unsigned char* lds, const u16* A, int lda, const u16* Bt, int K, u16* O, int ldc, int nunits) {
;     ...
;         const bool has_next = next_unit(ui + 1, nunits, nxt);
;         const char* nA = has_next ? (const char*)A + (size_t)nxt.pm * tstepA : cA; const char* nB = has_next ? (const char*)Bt + (size_t)nxt.pn * tstepB : cB;
;         for (int t = 0; t < nt; t += 2) {
;             const bool last = (t == nt - 2);
;             const char* a1 = cA + akb(t + 1);
;             const char* a2 = last ? nA + akb(0) : cA + akb(t + 2); const char* b2 = last ? nB : cB + (size_t)(t + 2) * kstep;
;             const char* a3 = last ? nA + akb(1) : cA + akb(t + 3); const char* b3 = b2 + kstep;
;             PG8_LDB(B0, 0, 0); PG8_SCHED; PG8_LDA(At, 0, 0); PG8_STAGE(PG8_SA(1, 1), a1 + hstepA, voffA);
;             PG8_WAIT_L(8); PG8_BAR; PG8_WAIT_L(0); PG8_MMA(0, 0, At, B0); PG8_BAR; PG8_SCHED;
;             PG8_LDB(B1, 0, 1); PG8_STAGE(PG8_SB(0, 0), b2, voffB);
;             PG8_BAR; PG8_WAIT_L(0); PG8_MMA(0, 1, At, B1); PG8_BAR;
.LBB0_136:
	s_ashr_i32 s5, s4, 31
	s_lshl_b64 s[12:13], s[4:5], 19
	s_add_u32 s12, s3, s12
	s_addc_u32 s13, s24, s13
	s_and_b64 s[14:15], s[22:23], exec
	s_cselect_b32 s5, s13, s11
	s_cselect_b32 s46, s12, s10
	s_ashr_i32 s7, s6, 31
	s_lshl_b64 s[14:15], s[6:7], 19
	s_add_u32 s14, s16, s14
	s_addc_u32 s15, s25, s15
	s_and_b64 s[22:23], s[22:23], exec
	s_cselect_b32 s7, s15, s21
	s_cselect_b32 s47, s14, s20
	s_add_u32 s49, s46, 0x80
	s_addc_u32 s50, s5, 0
	s_add_u32 s51, s20, 0x100
	s_addc_u32 s54, s21, 0
	s_add_u32 s22, s10, 0x40080
	s_addc_u32 s23, s11, 0
	s_mov_b32 s55, -2
	s_mov_b64 s[20:21], 0
	v_lshl_add_u64 v[140:141], s[22:23], 0, v[136:137]
	v_lshl_add_u64 v[142:143], s[22:23], 0, v[138:139]
	s_add_u32 s22, s10, s20
	s_addc_u32 s23, s11, s21
	s_add_u32 s30, s22, 0x100
	s_addc_u32 s31, s23, 0
	s_add_u32 s56, s51, s20
	s_addc_u32 s57, s54, s21
	s_add_u32 s22, s22, 0x180
	s_addc_u32 s23, s23, 0
	s_add_i32 s58, 0, 0x10000
	v_add_u32_e32 v160, s58, v145
	ds_read_b128 v[148:151], v160
	ds_read_b128 v[152:155], v160 offset:1024
	ds_read_b128 v[156:159], v160 offset:2048
	ds_read_b128 v[160:163], v160 offset:3072
	s_cmpk_eq_i32 s20, 0x700
	s_cselect_b32 s29, s50, s23
	s_cselect_b32 s28, s49, s22
	s_cselect_b32 s23, s7, s57
	s_cselect_b32 s22, s47, s56
	s_cselect_b32 s31, s5, s31
	s_cselect_b32 s30, s46, s30
	v_lshl_add_u64 v[172:173], v[142:143], 0, s[20:21]
	s_add_i32 m0, s27, 0xc000
	ds_read_b128 v[164:167], v147
	ds_read_b128 v[168:171], v147 offset:1024
	ds_read_b128 v[192:195], v147 offset:2048
	ds_read_b128 v[196:199], v147 offset:3072
	ds_read_b128 v[200:203], v147 offset:4096
	ds_read_b128 v[204:207], v147 offset:5120
	ds_read_b128 v[208:211], v147 offset:6144
	ds_read_b128 v[212:215], v147 offset:7168
	global_load_lds_dwordx4 v[172:173], off
	v_lshl_add_u64 v[172:173], v[140:141], 0, s[20:21]
	s_add_i32 m0, s27, 0xe000
	s_nop 0
	global_load_lds_dwordx4 v[172:173], off
	s_waitcnt lgkmcnt(8)
	s_barrier
	s_waitcnt lgkmcnt(0)
	s_waitcnt lgkmcnt(0)
	v_mfma_f32_16x16x32_bf16 v[126:129], v[148:151], v[164:167], 0
	v_mfma_f32_16x16x32_bf16 v[122:125], v[156:159], v[164:167], 0
	v_mfma_f32_16x16x32_bf16 v[118:121], v[148:151], v[192:195], 0
	v_mfma_f32_16x16x32_bf16 v[114:117], v[156:159], v[192:195], 0
	v_mfma_f32_16x16x32_bf16 v[102:105], v[148:151], v[200:203], 0
	v_mfma_f32_16x16x32_bf16 v[98:101], v[156:159], v[200:203], 0
	v_mfma_f32_16x16x32_bf16 v[86:89], v[148:151], v[208:211], 0
	v_mfma_f32_16x16x32_bf16 v[82:85], v[156:159], v[208:211], 0
	v_mfma_f32_16x16x32_bf16 v[126:129], v[152:155], v[168:171], v[126:129]
	v_mfma_f32_16x16x32_bf16 v[122:125], v[160:163], v[168:171], v[122:125]
	v_mfma_f32_16x16x32_bf16 v[118:121], v[152:155], v[196:199], v[118:121]
	v_mfma_f32_16x16x32_bf16 v[114:117], v[160:163], v[196:199], v[114:117]
	v_mfma_f32_16x16x32_bf16 v[102:105], v[152:155], v[204:207], v[102:105]
	v_mfma_f32_16x16x32_bf16 v[98:101], v[160:163], v[204:207], v[98:101]
	v_mfma_f32_16x16x32_bf16 v[86:89], v[152:155], v[212:215], v[86:89]
	v_mfma_f32_16x16x32_bf16 v[82:85], v[160:163], v[212:215], v[82:85]
	s_barrier
	s_add_i32 s59, 0, 0x14000
	v_add_u32_e32 v172, s59, v145
	s_add_i32 s56, s58, s26
	ds_read_b128 v[216:219], v172
	ds_read_b128 v[220:223], v172 offset:1024
	ds_read_b128 v[224:227], v172 offset:2048
	ds_read_b128 v[228:231], v172 offset:3072
	v_lshl_add_u64 v[172:173], s[22:23], 0, v[0:1]
	s_mov_b32 m0, s56
	v_lshl_add_u64 v[232:233], s[22:23], 0, v[130:131]
	global_load_lds_dwordx4 v[172:173], off
	s_add_i32 m0, s56, 0x2000
	s_nop 0
	global_load_lds_dwordx4 v[232:233], off
	s_barrier
	s_waitcnt lgkmcnt(0)
	s_waitcnt lgkmcnt(0)
	v_mfma_f32_16x16x32_bf16 v[110:113], v[216:219], v[164:167], 0
	v_mfma_f32_16x16x32_bf16 v[106:109], v[224:227], v[164:167], 0
	v_mfma_f32_16x16x32_bf16 v[94:97], v[216:219], v[192:195], 0
	v_mfma_f32_16x16x32_bf16 v[90:93], v[224:227], v[192:195], 0
	v_mfma_f32_16x16x32_bf16 v[78:81], v[216:219], v[200:203], 0
	v_mfma_f32_16x16x32_bf16 v[74:77], v[224:227], v[200:203], 0
	v_mfma_f32_16x16x32_bf16 v[70:73], v[216:219], v[208:211], 0
	v_mfma_f32_16x16x32_bf16 v[66:69], v[224:227], v[208:211], 0
	v_mfma_f32_16x16x32_bf16 v[110:113], v[220:223], v[168:171], v[110:113]
	v_mfma_f32_16x16x32_bf16 v[106:109], v[228:231], v[168:171], v[106:109]
	v_mfma_f32_16x16x32_bf16 v[94:97], v[220:223], v[196:199], v[94:97]
	v_mfma_f32_16x16x32_bf16 v[90:93], v[228:231], v[196:199], v[90:93]
	v_mfma_f32_16x16x32_bf16 v[78:81], v[220:223], v[204:207], v[78:81]
	v_mfma_f32_16x16x32_bf16 v[74:77], v[228:231], v[204:207], v[74:77]
	v_mfma_f32_16x16x32_bf16 v[70:73], v[220:223], v[212:215], v[70:73]
	v_mfma_f32_16x16x32_bf16 v[66:69], v[228:231], v[212:215], v[66:69]
	s_mov_b32 m0, s27
	s_barrier
	ds_read_b128 v[164:167], v147 offset:16384
	ds_read_b128 v[168:171], v147 offset:17408
	ds_read_b128 v[192:195], v147 offset:18432
	ds_read_b128 v[196:199], v147 offset:19456
	ds_read_b128 v[200:203], v147 offset:20480
	ds_read_b128 v[204:207], v147 offset:21504
	ds_read_b128 v[208:211], v147 offset:22528
	ds_read_b128 v[212:215], v147 offset:23552
	global_load_lds_dwordx4 v134, s[30:31]
	s_mov_b32 m0, s34
	s_nop 0
	global_load_lds_dwordx4 v132, s[30:31]
	s_barrier
; #define PG8_STAGE(bufoff, gbase, voff) do { _Pragma("unroll") for (int _i = 0; _i < 2; ++_i) \
;         __builtin_amdgcn_global_load_lds((const unsigned*)((const char*)(gbase) + (voff)[_i]), (LAS unsigned*)(lds + (bufoff) + ldsw + _i * 8192), 16, 0, 0); } while (0)
; #define PG8_LDA(dst, b, h) do { _Pragma("unroll") for (int m = 0; m < 4; ++m) _Pragma("unroll") for (int k = 0; k < 2; ++k) dst[m][k] = *(const LAS bf16x8*)(lds + PG8_SA(b, h) + aoff + m * 2048 + k * 1024); } while (0)
; #define PG8_LDB(dst, b, h) do { _Pragma("unroll") for (int n = 0; n < 2; ++n) _Pragma("unroll") for (int k = 0; k < 2; ++k) dst[n][k] = *(const LAS bf16x8*)(lds + PG8_SB(b, h) + boff + n * 2048 + k * 1024); } while (0)
; #define PG8_MMA(ai, bj, At, Bt_) do { __builtin_amdgcn_s_setprio(1); _Pragma("unroll") for (int m = 0; m < 4; ++m) _Pragma("unroll") for (int n = 0; n < 2; ++n) _Pragma("unroll") for (int k = 0; k < 2; ++k) \
;         acc[ai][bj][m][n] = __builtin_amdgcn_mfma_f32_16x16x32_bf16(Bt_[n][k], At[m][k], acc[ai][bj][m][n], 0, 0, 0); __builtin_amdgcn_s_setprio(0); } while (0)
; #define PG8_WAIT_V(n) asm volatile("s_waitcnt vmcnt(" #n ")" ::: "memory")
; #define PG8_WAIT_L(n) asm volatile("s_waitcnt lgkmcnt(" #n ")" ::: "memory")
; #define PG8_BAR __builtin_amdgcn_s_barrier()
; #define PG8_SCHED __builtin_amdgcn_sched_barrier(0)
; template <bool REMAP>
; DI void gemm_phase(LAS unsigned char* lds, const u16* A, int lda, const u16* Bt, int K, u16* O, int ldc, int nunits) {
;     ...
;             PG8_BAR; PG8_WAIT_L(0); PG8_MMA(0, 1, At, B1); PG8_BAR;
;             PG8_LDA(At, 0, 1); PG8_STAGE(PG8_SA(0, 0), a2, voffA);
;             PG8_BAR; PG8_WAIT_L(0); PG8_MMA(1, 0, At, B0); PG8_BAR; PG8_SCHED;
;             PG8_STAGE(PG8_SB(0, 1), b2 + hstepB, voffB);
;             PG8_WAIT_V(6); PG8_BAR; PG8_MMA(1, 1, At, B1); PG8_BAR;
;             PG8_LDB(B0, 1, 0); PG8_SCHED; PG8_LDA(At, 1, 0); PG8_STAGE(PG8_SA(0, 1), a2 + hstepA, voffA);
;             PG8_WAIT_L(8); PG8_BAR; PG8_WAIT_L(0); PG8_MMA(0, 0, At, B0); PG8_BAR; PG8_SCHED;
;             PG8_LDB(B1, 1, 1); PG8_STAGE(PG8_SB(1, 0), b3, voffB);
;             PG8_BAR; PG8_WAIT_L(0); PG8_MMA(0, 1, At, B1); PG8_BAR;
	s_waitcnt lgkmcnt(0)
	s_waitcnt lgkmcnt(0)
	v_mfma_f32_16x16x32_bf16 v[62:65], v[148:151], v[164:167], 0
	v_mfma_f32_16x16x32_bf16 v[58:61], v[156:159], v[164:167], 0
	v_mfma_f32_16x16x32_bf16 v[54:57], v[148:151], v[192:195], 0
	v_mfma_f32_16x16x32_bf16 v[50:53], v[156:159], v[192:195], 0
	v_mfma_f32_16x16x32_bf16 v[38:41], v[148:151], v[200:203], 0
	v_mfma_f32_16x16x32_bf16 v[34:37], v[156:159], v[200:203], 0
	v_mfma_f32_16x16x32_bf16 v[22:25], v[148:151], v[208:211], 0
	v_mfma_f32_16x16x32_bf16 v[18:21], v[156:159], v[208:211], 0
	v_mfma_f32_16x16x32_bf16 v[62:65], v[152:155], v[168:171], v[62:65]
	v_mfma_f32_16x16x32_bf16 v[58:61], v[160:163], v[168:171], v[58:61]
	v_mfma_f32_16x16x32_bf16 v[54:57], v[152:155], v[196:199], v[54:57]
	v_mfma_f32_16x16x32_bf16 v[50:53], v[160:163], v[196:199], v[50:53]
	v_mfma_f32_16x16x32_bf16 v[38:41], v[152:155], v[204:207], v[38:41]
	v_mfma_f32_16x16x32_bf16 v[34:37], v[160:163], v[204:207], v[34:37]
	v_mfma_f32_16x16x32_bf16 v[22:25], v[152:155], v[212:215], v[22:25]
	v_mfma_f32_16x16x32_bf16 v[18:21], v[160:163], v[212:215], v[18:21]
	s_barrier
	s_add_u32 s56, s22, 0x40000
	s_addc_u32 s57, s23, 0
	s_add_i32 s58, s59, s26
	s_mov_b32 m0, s58
	s_nop 0
	global_load_lds_dwordx4 v0, s[56:57]
	s_add_i32 m0, s58, 0x2000
	s_nop 0
	global_load_lds_dwordx4 v130, s[56:57]
	s_waitcnt vmcnt(6)
	s_barrier
	v_mfma_f32_16x16x32_bf16 v[46:49], v[216:219], v[164:167], 0
	v_mfma_f32_16x16x32_bf16 v[42:45], v[224:227], v[164:167], 0
	v_mfma_f32_16x16x32_bf16 v[30:33], v[216:219], v[192:195], 0
	v_mfma_f32_16x16x32_bf16 v[26:29], v[224:227], v[192:195], 0
	v_mfma_f32_16x16x32_bf16 v[14:17], v[216:219], v[200:203], 0
	v_mfma_f32_16x16x32_bf16 v[10:13], v[224:227], v[200:203], 0
	v_mfma_f32_16x16x32_bf16 v[6:9], v[216:219], v[208:211], 0
	v_mfma_f32_16x16x32_bf16 v[2:5], v[224:227], v[208:211], 0
	v_mfma_f32_16x16x32_bf16 v[46:49], v[220:223], v[168:171], v[46:49]
	v_mfma_f32_16x16x32_bf16 v[42:45], v[228:231], v[168:171], v[42:45]
	v_mfma_f32_16x16x32_bf16 v[30:33], v[220:223], v[196:199], v[30:33]
	v_mfma_f32_16x16x32_bf16 v[26:29], v[228:231], v[196:199], v[26:29]
	v_mfma_f32_16x16x32_bf16 v[14:17], v[220:223], v[204:207], v[14:17]
	v_mfma_f32_16x16x32_bf16 v[10:13], v[228:231], v[204:207], v[10:13]
	v_mfma_f32_16x16x32_bf16 v[6:9], v[220:223], v[212:215], v[6:9]
	v_mfma_f32_16x16x32_bf16 v[2:5], v[228:231], v[212:215], v[2:5]
	s_add_i32 s56, 0, 0x18000
	v_add_u32_e32 v160, s56, v145
	s_barrier
	ds_read_b128 v[148:151], v160
	ds_read_b128 v[152:155], v160 offset:1024
	ds_read_b128 v[156:159], v160 offset:2048
	ds_read_b128 v[160:163], v160 offset:3072
	s_add_u32 s30, s30, 0x40000
	s_addc_u32 s31, s31, 0
	s_mov_b32 m0, s35
	ds_read_b128 v[164:167], v147 offset:32768
	ds_read_b128 v[168:171], v147 offset:33792
	ds_read_b128 v[192:195], v147 offset:34816
	ds_read_b128 v[196:199], v147 offset:35840
	ds_read_b128 v[200:203], v147 offset:36864
	ds_read_b128 v[204:207], v147 offset:37888
	ds_read_b128 v[208:211], v147 offset:38912
	ds_read_b128 v[212:215], v147 offset:39936
	global_load_lds_dwordx4 v134, s[30:31]
	s_mov_b32 m0, s36
	s_nop 0
	global_load_lds_dwordx4 v132, s[30:31]
	s_waitcnt lgkmcnt(8)
	s_barrier
	s_waitcnt lgkmcnt(0)
	s_waitcnt lgkmcnt(0)
	v_mfma_f32_16x16x32_bf16 v[126:129], v[148:151], v[164:167], v[126:129]
	v_mfma_f32_16x16x32_bf16 v[122:125], v[156:159], v[164:167], v[122:125]
	v_mfma_f32_16x16x32_bf16 v[118:121], v[148:151], v[192:195], v[118:121]
	v_mfma_f32_16x16x32_bf16 v[114:117], v[156:159], v[192:195], v[114:117]
	v_mfma_f32_16x16x32_bf16 v[102:105], v[148:151], v[200:203], v[102:105]
	v_mfma_f32_16x16x32_bf16 v[98:101], v[156:159], v[200:203], v[98:101]
	v_mfma_f32_16x16x32_bf16 v[86:89], v[148:151], v[208:211], v[86:89]
	v_mfma_f32_16x16x32_bf16 v[82:85], v[156:159], v[208:211], v[82:85]
	v_mfma_f32_16x16x32_bf16 v[126:129], v[152:155], v[168:171], v[126:129]
	v_mfma_f32_16x16x32_bf16 v[122:125], v[160:163], v[168:171], v[122:125]
	v_mfma_f32_16x16x32_bf16 v[118:121], v[152:155], v[196:199], v[118:121]
	v_mfma_f32_16x16x32_bf16 v[114:117], v[160:163], v[196:199], v[114:117]
	v_mfma_f32_16x16x32_bf16 v[102:105], v[152:155], v[204:207], v[102:105]
	v_mfma_f32_16x16x32_bf16 v[98:101], v[160:163], v[204:207], v[98:101]
	v_mfma_f32_16x16x32_bf16 v[86:89], v[152:155], v[212:215], v[86:89]
	v_mfma_f32_16x16x32_bf16 v[82:85], v[160:163], v[212:215], v[82:85]
	s_barrier
	s_add_i32 s30, 0, 0x1c000
	s_add_i32 s31, s56, s26
	v_add_u32_e32 v228, s30, v145
	v_lshl_add_u64 v[172:173], v[172:173], 0, s[18:19]
	s_mov_b32 m0, s31
	ds_read_b128 v[216:219], v228
	ds_read_b128 v[220:223], v228 offset:1024
	ds_read_b128 v[224:227], v228 offset:2048
	ds_read_b128 v[228:231], v228 offset:3072
	global_load_lds_dwordx4 v[172:173], off
	v_lshl_add_u64 v[172:173], v[232:233], 0, s[18:19]
	s_add_i32 m0, s31, 0x2000
	s_nop 0
	global_load_lds_dwordx4 v[172:173], off
	s_barrier
	s_waitcnt lgkmcnt(0)
	s_waitcnt lgkmcnt(0)
	v_mfma_f32_16x16x32_bf16 v[110:113], v[216:219], v[164:167], v[110:113]
	v_mfma_f32_16x16x32_bf16 v[106:109], v[224:227], v[164:167], v[106:109]
	v_mfma_f32_16x16x32_bf16 v[94:97], v[216:219], v[192:195], v[94:97]
	v_mfma_f32_16x16x32_bf16 v[90:93], v[224:227], v[192:195], v[90:93]
	v_mfma_f32_16x16x32_bf16 v[78:81], v[216:219], v[200:203], v[78:81]
	v_mfma_f32_16x16x32_bf16 v[74:77], v[224:227], v[200:203], v[74:77]
	v_mfma_f32_16x16x32_bf16 v[70:73], v[216:219], v[208:211], v[70:73]
	v_mfma_f32_16x16x32_bf16 v[66:69], v[224:227], v[208:211], v[66:69]
	v_mfma_f32_16x16x32_bf16 v[110:113], v[220:223], v[168:171], v[110:113]
	v_mfma_f32_16x16x32_bf16 v[106:109], v[228:231], v[168:171], v[106:109]
	v_mfma_f32_16x16x32_bf16 v[94:97], v[220:223], v[196:199], v[94:97]
	v_mfma_f32_16x16x32_bf16 v[90:93], v[228:231], v[196:199], v[90:93]
	v_mfma_f32_16x16x32_bf16 v[78:81], v[220:223], v[204:207], v[78:81]
	v_mfma_f32_16x16x32_bf16 v[74:77], v[228:231], v[204:207], v[74:77]
	v_mfma_f32_16x16x32_bf16 v[70:73], v[220:223], v[212:215], v[70:73]
	v_mfma_f32_16x16x32_bf16 v[66:69], v[228:231], v[212:215], v[66:69]
	s_mov_b32 m0, s37
	s_barrier
; #define PG8_STAGE(bufoff, gbase, voff) do { _Pragma("unroll") for (int _i = 0; _i < 2; ++_i) \
;         __builtin_amdgcn_global_load_lds((const unsigned*)((const char*)(gbase) + (voff)[_i]), (LAS unsigned*)(lds + (bufoff) + ldsw + _i * 8192), 16, 0, 0); } while (0)
; #define PG8_LDA(dst, b, h) do { _Pragma("unroll") for (int m = 0; m < 4; ++m) _Pragma("unroll") for (int k = 0; k < 2; ++k) dst[m][k] = *(const LAS bf16x8*)(lds + PG8_SA(b, h) + aoff + m * 2048 + k * 1024); } while (0)
; #define PG8_LDB(dst, b, h) do { _Pragma("unroll") for (int n = 0; n < 2; ++n) _Pragma("unroll") for (int k = 0; k < 2; ++k) dst[n][k] = *(const LAS bf16x8*)(lds + PG8_SB(b, h) + boff + n * 2048 + k * 1024); } while (0)
; #define PG8_MMA(ai, bj, At, Bt_) do { __builtin_amdgcn_s_setprio(1); _Pragma("unroll") for (int m = 0; m < 4; ++m) _Pragma("unroll") for (int n = 0; n < 2; ++n) _Pragma("unroll") for (int k = 0; k < 2; ++k) \
;         acc[ai][bj][m][n] = __builtin_amdgcn_mfma_f32_16x16x32_bf16(Bt_[n][k], At[m][k], acc[ai][bj][m][n], 0, 0, 0); __builtin_amdgcn_s_setprio(0); } while (0)
; #define PG8_WAIT_V(n) asm volatile("s_waitcnt vmcnt(" #n ")" ::: "memory")
; #define PG8_WAIT_L(n) asm volatile("s_waitcnt lgkmcnt(" #n ")" ::: "memory")
; #define PG8_BAR __builtin_amdgcn_s_barrier()
; template <bool REMAP>
; DI void gemm_phase(LAS unsigned char* lds, const u16* A, int lda, const u16* Bt, int K, u16* O, int ldc, int nunits) {
;     ...
;         for (int t = 0; t < nt; t += 2) {
;             const bool last = (t == nt - 2);
;             const char* a1 = cA + akb(t + 1);
;             const char* a2 = last ? nA + akb(0) : cA + akb(t + 2); const char* b2 = last ? nB : cB + (size_t)(t + 2) * kstep;
;             const char* a3 = last ? nA + akb(1) : cA + akb(t + 3); const char* b3 = b2 + kstep;
;             PG8_LDB(B0, 0, 0); PG8_SCHED; PG8_LDA(At, 0, 0); PG8_STAGE(PG8_SA(1, 1), a1 + hstepA, voffA);
;             PG8_WAIT_L(8); PG8_BAR; PG8_WAIT_L(0); PG8_MMA(0, 0, At, B0); PG8_BAR; PG8_SCHED;
;     ...
;             PG8_BAR; PG8_WAIT_L(0); PG8_MMA(0, 1, At, B1); PG8_BAR;
;             PG8_LDA(At, 1, 1); PG8_STAGE(PG8_SA(1, 0), a3, voffA);
;             PG8_BAR; PG8_WAIT_L(0); PG8_MMA(1, 0, At, B0); PG8_BAR; PG8_SCHED;
;             PG8_STAGE(PG8_SB(1, 1), b3 + hstepB, voffB);
;             PG8_WAIT_V(6); PG8_BAR; PG8_MMA(1, 1, At, B1); PG8_BAR;
	ds_read_b128 v[164:167], v147 offset:49152
	ds_read_b128 v[168:171], v147 offset:50176
	ds_read_b128 v[192:195], v147 offset:51200
	ds_read_b128 v[196:199], v147 offset:52224
	ds_read_b128 v[200:203], v147 offset:53248
	ds_read_b128 v[204:207], v147 offset:54272
	ds_read_b128 v[208:211], v147 offset:55296
	ds_read_b128 v[212:215], v147 offset:56320
	global_load_lds_dwordx4 v134, s[28:29]
	s_mov_b32 m0, s38
	s_nop 0
	global_load_lds_dwordx4 v132, s[28:29]
	s_barrier
	s_waitcnt lgkmcnt(0)
	s_waitcnt lgkmcnt(0)
	v_mfma_f32_16x16x32_bf16 v[62:65], v[148:151], v[164:167], v[62:65]
	v_mfma_f32_16x16x32_bf16 v[58:61], v[156:159], v[164:167], v[58:61]
	v_mfma_f32_16x16x32_bf16 v[54:57], v[148:151], v[192:195], v[54:57]
	v_mfma_f32_16x16x32_bf16 v[50:53], v[156:159], v[192:195], v[50:53]
	v_mfma_f32_16x16x32_bf16 v[38:41], v[148:151], v[200:203], v[38:41]
	v_mfma_f32_16x16x32_bf16 v[34:37], v[156:159], v[200:203], v[34:37]
	v_mfma_f32_16x16x32_bf16 v[22:25], v[148:151], v[208:211], v[22:25]
	v_mfma_f32_16x16x32_bf16 v[18:21], v[156:159], v[208:211], v[18:21]
	v_mfma_f32_16x16x32_bf16 v[62:65], v[152:155], v[168:171], v[62:65]
	v_mfma_f32_16x16x32_bf16 v[58:61], v[160:163], v[168:171], v[58:61]
	v_mfma_f32_16x16x32_bf16 v[54:57], v[152:155], v[196:199], v[54:57]
	v_mfma_f32_16x16x32_bf16 v[50:53], v[160:163], v[196:199], v[50:53]
	v_mfma_f32_16x16x32_bf16 v[38:41], v[152:155], v[204:207], v[38:41]
	v_mfma_f32_16x16x32_bf16 v[34:37], v[160:163], v[204:207], v[34:37]
	v_mfma_f32_16x16x32_bf16 v[22:25], v[152:155], v[212:215], v[22:25]
	v_mfma_f32_16x16x32_bf16 v[18:21], v[160:163], v[212:215], v[18:21]
	s_barrier
	s_add_u32 s22, s22, 0x40080
	s_addc_u32 s23, s23, 0
	s_add_i32 s28, s30, s26
	s_mov_b32 m0, s28
	s_nop 0
	global_load_lds_dwordx4 v0, s[22:23]
	s_add_i32 m0, s28, 0x2000
	s_nop 0
	global_load_lds_dwordx4 v130, s[22:23]
	s_waitcnt vmcnt(6)
	s_barrier
	v_mfma_f32_16x16x32_bf16 v[46:49], v[216:219], v[164:167], v[46:49]
	v_mfma_f32_16x16x32_bf16 v[42:45], v[224:227], v[164:167], v[42:45]
	v_mfma_f32_16x16x32_bf16 v[30:33], v[216:219], v[192:195], v[30:33]
	v_mfma_f32_16x16x32_bf16 v[26:29], v[224:227], v[192:195], v[26:29]
	v_mfma_f32_16x16x32_bf16 v[14:17], v[216:219], v[200:203], v[14:17]
	v_mfma_f32_16x16x32_bf16 v[10:13], v[224:227], v[200:203], v[10:13]
	v_mfma_f32_16x16x32_bf16 v[6:9], v[216:219], v[208:211], v[6:9]
	v_mfma_f32_16x16x32_bf16 v[2:5], v[224:227], v[208:211], v[2:5]
	v_mfma_f32_16x16x32_bf16 v[46:49], v[220:223], v[168:171], v[46:49]
	v_mfma_f32_16x16x32_bf16 v[42:45], v[228:231], v[168:171], v[42:45]
	v_mfma_f32_16x16x32_bf16 v[30:33], v[220:223], v[196:199], v[30:33]
	v_mfma_f32_16x16x32_bf16 v[26:29], v[228:231], v[196:199], v[26:29]
	v_mfma_f32_16x16x32_bf16 v[14:17], v[220:223], v[204:207], v[14:17]
	v_mfma_f32_16x16x32_bf16 v[10:13], v[228:231], v[204:207], v[10:13]
	v_mfma_f32_16x16x32_bf16 v[6:9], v[220:223], v[212:215], v[6:9]
	v_mfma_f32_16x16x32_bf16 v[2:5], v[228:231], v[212:215], v[2:5]
	s_add_i32 s55, s55, 2
	s_add_u32 s20, s20, 0x100
	s_addc_u32 s21, s21, 0
	s_cmp_gt_u32 s55, 13
	s_barrier
.LBB0_137:
	s_add_u32 s22, s10, s20
	s_addc_u32 s23, s11, s21
	s_add_u32 s30, s22, 0x100
	s_addc_u32 s31, s23, 0
	s_add_u32 s56, s51, s20
	s_addc_u32 s57, s54, s21
	s_add_u32 s22, s22, 0x180
	s_addc_u32 s23, s23, 0
	s_add_i32 s58, 0, 0x10000
	v_add_u32_e32 v160, s58, v145
	ds_read_b128 v[148:151], v160
	ds_read_b128 v[152:155], v160 offset:1024
	ds_read_b128 v[156:159], v160 offset:2048
	ds_read_b128 v[160:163], v160 offset:3072
	s_cmpk_eq_i32 s20, 0x700
	s_cselect_b32 s29, s50, s23
	s_cselect_b32 s28, s49, s22
	s_cselect_b32 s23, s7, s57
	s_cselect_b32 s22, s47, s56
	s_cselect_b32 s31, s5, s31
	s_cselect_b32 s30, s46, s30
	v_lshl_add_u64 v[172:173], v[142:143], 0, s[20:21]
	s_add_i32 m0, s27, 0xc000
	ds_read_b128 v[164:167], v147
	ds_read_b128 v[168:171], v147 offset:1024
	ds_read_b128 v[192:195], v147 offset:2048
	ds_read_b128 v[196:199], v147 offset:3072
	ds_read_b128 v[200:203], v147 offset:4096
	ds_read_b128 v[204:207], v147 offset:5120
	ds_read_b128 v[208:211], v147 offset:6144
	ds_read_b128 v[212:215], v147 offset:7168
	global_load_lds_dwordx4 v[172:173], off
	v_lshl_add_u64 v[172:173], v[140:141], 0, s[20:21]
	s_add_i32 m0, s27, 0xe000
	s_nop 0
	global_load_lds_dwordx4 v[172:173], off
	s_waitcnt lgkmcnt(8)
	s_barrier
	s_waitcnt lgkmcnt(0)
	s_waitcnt lgkmcnt(0)
	v_mfma_f32_16x16x32_bf16 v[126:129], v[148:151], v[164:167], v[126:129]
	v_mfma_f32_16x16x32_bf16 v[122:125], v[156:159], v[164:167], v[122:125]
	v_mfma_f32_16x16x32_bf16 v[118:121], v[148:151], v[192:195], v[118:121]
	v_mfma_f32_16x16x32_bf16 v[114:117], v[156:159], v[192:195], v[114:117]
	v_mfma_f32_16x16x32_bf16 v[102:105], v[148:151], v[200:203], v[102:105]
	v_mfma_f32_16x16x32_bf16 v[98:101], v[156:159], v[200:203], v[98:101]
	v_mfma_f32_16x16x32_bf16 v[86:89], v[148:151], v[208:211], v[86:89]
	v_mfma_f32_16x16x32_bf16 v[82:85], v[156:159], v[208:211], v[82:85]
	v_mfma_f32_16x16x32_bf16 v[126:129], v[152:155], v[168:171], v[126:129]
	v_mfma_f32_16x16x32_bf16 v[122:125], v[160:163], v[168:171], v[122:125]
	v_mfma_f32_16x16x32_bf16 v[118:121], v[152:155], v[196:199], v[118:121]
	v_mfma_f32_16x16x32_bf16 v[114:117], v[160:163], v[196:199], v[114:117]
	v_mfma_f32_16x16x32_bf16 v[102:105], v[152:155], v[204:207], v[102:105]
	v_mfma_f32_16x16x32_bf16 v[98:101], v[160:163], v[204:207], v[98:101]
	v_mfma_f32_16x16x32_bf16 v[86:89], v[152:155], v[212:215], v[86:89]
	v_mfma_f32_16x16x32_bf16 v[82:85], v[160:163], v[212:215], v[82:85]
	s_barrier
; #define PG8_STAGE(bufoff, gbase, voff) do { _Pragma("unroll") for (int _i = 0; _i < 2; ++_i) \
;         __builtin_amdgcn_global_load_lds((const unsigned*)((const char*)(gbase) + (voff)[_i]), (LAS unsigned*)(lds + (bufoff) + ldsw + _i * 8192), 16, 0, 0); } while (0)
; #define PG8_LDA(dst, b, h) do { _Pragma("unroll") for (int m = 0; m < 4; ++m) _Pragma("unroll") for (int k = 0; k < 2; ++k) dst[m][k] = *(const LAS bf16x8*)(lds + PG8_SA(b, h) + aoff + m * 2048 + k * 1024); } while (0)
; #define PG8_LDB(dst, b, h) do { _Pragma("unroll") for (int n = 0; n < 2; ++n) _Pragma("unroll") for (int k = 0; k < 2; ++k) dst[n][k] = *(const LAS bf16x8*)(lds + PG8_SB(b, h) + boff + n * 2048 + k * 1024); } while (0)
; #define PG8_MMA(ai, bj, At, Bt_) do { __builtin_amdgcn_s_setprio(1); _Pragma("unroll") for (int m = 0; m < 4; ++m) _Pragma("unroll") for (int n = 0; n < 2; ++n) _Pragma("unroll") for (int k = 0; k < 2; ++k) \
;         acc[ai][bj][m][n] = __builtin_amdgcn_mfma_f32_16x16x32_bf16(Bt_[n][k], At[m][k], acc[ai][bj][m][n], 0, 0, 0); __builtin_amdgcn_s_setprio(0); } while (0)
; #define PG8_WAIT_V(n) asm volatile("s_waitcnt vmcnt(" #n ")" ::: "memory")
; #define PG8_WAIT_L(n) asm volatile("s_waitcnt lgkmcnt(" #n ")" ::: "memory")
; #define PG8_BAR __builtin_amdgcn_s_barrier()
; #define PG8_SCHED __builtin_amdgcn_sched_barrier(0)
; template <bool REMAP>
; DI void gemm_phase(LAS unsigned char* lds, const u16* A, int lda, const u16* Bt, int K, u16* O, int ldc, int nunits) {
;     ...
;             PG8_WAIT_L(8); PG8_BAR; PG8_WAIT_L(0); PG8_MMA(0, 0, At, B0); PG8_BAR; PG8_SCHED;
;             PG8_LDB(B1, 0, 1); PG8_STAGE(PG8_SB(0, 0), b2, voffB);
;             PG8_BAR; PG8_WAIT_L(0); PG8_MMA(0, 1, At, B1); PG8_BAR;
;             PG8_LDA(At, 0, 1); PG8_STAGE(PG8_SA(0, 0), a2, voffA);
;             PG8_BAR; PG8_WAIT_L(0); PG8_MMA(1, 0, At, B0); PG8_BAR; PG8_SCHED;
;             PG8_STAGE(PG8_SB(0, 1), b2 + hstepB, voffB);
;             PG8_WAIT_V(6); PG8_BAR; PG8_MMA(1, 1, At, B1); PG8_BAR;
;             PG8_LDB(B0, 1, 0); PG8_SCHED; PG8_LDA(At, 1, 0); PG8_STAGE(PG8_SA(0, 1), a2 + hstepA, voffA);
;             PG8_WAIT_L(8); PG8_BAR; PG8_WAIT_L(0); PG8_MMA(0, 0, At, B0); PG8_BAR; PG8_SCHED;
	s_add_i32 s59, 0, 0x14000
	v_add_u32_e32 v172, s59, v145
	s_add_i32 s56, s58, s26
	ds_read_b128 v[216:219], v172
	ds_read_b128 v[220:223], v172 offset:1024
	ds_read_b128 v[224:227], v172 offset:2048
	ds_read_b128 v[228:231], v172 offset:3072
	v_lshl_add_u64 v[172:173], s[22:23], 0, v[0:1]
	s_mov_b32 m0, s56
	v_lshl_add_u64 v[232:233], s[22:23], 0, v[130:131]
	global_load_lds_dwordx4 v[172:173], off
	s_add_i32 m0, s56, 0x2000
	s_nop 0
	global_load_lds_dwordx4 v[232:233], off
	s_barrier
	s_waitcnt lgkmcnt(0)
	s_waitcnt lgkmcnt(0)
	v_mfma_f32_16x16x32_bf16 v[110:113], v[216:219], v[164:167], v[110:113]
	v_mfma_f32_16x16x32_bf16 v[106:109], v[224:227], v[164:167], v[106:109]
	v_mfma_f32_16x16x32_bf16 v[94:97], v[216:219], v[192:195], v[94:97]
	v_mfma_f32_16x16x32_bf16 v[90:93], v[224:227], v[192:195], v[90:93]
	v_mfma_f32_16x16x32_bf16 v[78:81], v[216:219], v[200:203], v[78:81]
	v_mfma_f32_16x16x32_bf16 v[74:77], v[224:227], v[200:203], v[74:77]
	v_mfma_f32_16x16x32_bf16 v[70:73], v[216:219], v[208:211], v[70:73]
	v_mfma_f32_16x16x32_bf16 v[66:69], v[224:227], v[208:211], v[66:69]
	v_mfma_f32_16x16x32_bf16 v[110:113], v[220:223], v[168:171], v[110:113]
	v_mfma_f32_16x16x32_bf16 v[106:109], v[228:231], v[168:171], v[106:109]
	v_mfma_f32_16x16x32_bf16 v[94:97], v[220:223], v[196:199], v[94:97]
	v_mfma_f32_16x16x32_bf16 v[90:93], v[228:231], v[196:199], v[90:93]
	v_mfma_f32_16x16x32_bf16 v[78:81], v[220:223], v[204:207], v[78:81]
	v_mfma_f32_16x16x32_bf16 v[74:77], v[228:231], v[204:207], v[74:77]
	v_mfma_f32_16x16x32_bf16 v[70:73], v[220:223], v[212:215], v[70:73]
	v_mfma_f32_16x16x32_bf16 v[66:69], v[228:231], v[212:215], v[66:69]
	s_mov_b32 m0, s27
	s_barrier
	ds_read_b128 v[164:167], v147 offset:16384
	ds_read_b128 v[168:171], v147 offset:17408
	ds_read_b128 v[192:195], v147 offset:18432
	ds_read_b128 v[196:199], v147 offset:19456
	ds_read_b128 v[200:203], v147 offset:20480
	ds_read_b128 v[204:207], v147 offset:21504
	ds_read_b128 v[208:211], v147 offset:22528
	ds_read_b128 v[212:215], v147 offset:23552
	global_load_lds_dwordx4 v134, s[30:31]
	s_mov_b32 m0, s34
	s_nop 0
	global_load_lds_dwordx4 v132, s[30:31]
	s_barrier
	s_waitcnt lgkmcnt(0)
	s_waitcnt lgkmcnt(0)
	v_mfma_f32_16x16x32_bf16 v[62:65], v[148:151], v[164:167], v[62:65]
	v_mfma_f32_16x16x32_bf16 v[58:61], v[156:159], v[164:167], v[58:61]
	v_mfma_f32_16x16x32_bf16 v[54:57], v[148:151], v[192:195], v[54:57]
	v_mfma_f32_16x16x32_bf16 v[50:53], v[156:159], v[192:195], v[50:53]
	v_mfma_f32_16x16x32_bf16 v[38:41], v[148:151], v[200:203], v[38:41]
	v_mfma_f32_16x16x32_bf16 v[34:37], v[156:159], v[200:203], v[34:37]
	v_mfma_f32_16x16x32_bf16 v[22:25], v[148:151], v[208:211], v[22:25]
	v_mfma_f32_16x16x32_bf16 v[18:21], v[156:159], v[208:211], v[18:21]
	v_mfma_f32_16x16x32_bf16 v[62:65], v[152:155], v[168:171], v[62:65]
	v_mfma_f32_16x16x32_bf16 v[58:61], v[160:163], v[168:171], v[58:61]
	v_mfma_f32_16x16x32_bf16 v[54:57], v[152:155], v[196:199], v[54:57]
	v_mfma_f32_16x16x32_bf16 v[50:53], v[160:163], v[196:199], v[50:53]
	v_mfma_f32_16x16x32_bf16 v[38:41], v[152:155], v[204:207], v[38:41]
	v_mfma_f32_16x16x32_bf16 v[34:37], v[160:163], v[204:207], v[34:37]
	v_mfma_f32_16x16x32_bf16 v[22:25], v[152:155], v[212:215], v[22:25]
	v_mfma_f32_16x16x32_bf16 v[18:21], v[160:163], v[212:215], v[18:21]
	s_barrier
	s_add_u32 s56, s22, 0x40000
	s_addc_u32 s57, s23, 0
	s_add_i32 s58, s59, s26
	s_mov_b32 m0, s58
	s_nop 0
	global_load_lds_dwordx4 v0, s[56:57]
	s_add_i32 m0, s58, 0x2000
	s_nop 0
	global_load_lds_dwordx4 v130, s[56:57]
	s_waitcnt vmcnt(6)
	s_barrier
	v_mfma_f32_16x16x32_bf16 v[46:49], v[216:219], v[164:167], v[46:49]
	v_mfma_f32_16x16x32_bf16 v[42:45], v[224:227], v[164:167], v[42:45]
	v_mfma_f32_16x16x32_bf16 v[30:33], v[216:219], v[192:195], v[30:33]
	v_mfma_f32_16x16x32_bf16 v[26:29], v[224:227], v[192:195], v[26:29]
	v_mfma_f32_16x16x32_bf16 v[14:17], v[216:219], v[200:203], v[14:17]
	v_mfma_f32_16x16x32_bf16 v[10:13], v[224:227], v[200:203], v[10:13]
	v_mfma_f32_16x16x32_bf16 v[6:9], v[216:219], v[208:211], v[6:9]
	v_mfma_f32_16x16x32_bf16 v[2:5], v[224:227], v[208:211], v[2:5]
	v_mfma_f32_16x16x32_bf16 v[46:49], v[220:223], v[168:171], v[46:49]
	v_mfma_f32_16x16x32_bf16 v[42:45], v[228:231], v[168:171], v[42:45]
	v_mfma_f32_16x16x32_bf16 v[30:33], v[220:223], v[196:199], v[30:33]
	v_mfma_f32_16x16x32_bf16 v[26:29], v[228:231], v[196:199], v[26:29]
	v_mfma_f32_16x16x32_bf16 v[14:17], v[220:223], v[204:207], v[14:17]
	v_mfma_f32_16x16x32_bf16 v[10:13], v[228:231], v[204:207], v[10:13]
	v_mfma_f32_16x16x32_bf16 v[6:9], v[220:223], v[212:215], v[6:9]
	v_mfma_f32_16x16x32_bf16 v[2:5], v[228:231], v[212:215], v[2:5]
	s_add_i32 s56, 0, 0x18000
	v_add_u32_e32 v160, s56, v145
	s_barrier
	ds_read_b128 v[148:151], v160
	ds_read_b128 v[152:155], v160 offset:1024
	ds_read_b128 v[156:159], v160 offset:2048
	ds_read_b128 v[160:163], v160 offset:3072
	s_add_u32 s30, s30, 0x40000
	s_addc_u32 s31, s31, 0
	s_mov_b32 m0, s35
	ds_read_b128 v[164:167], v147 offset:32768
	ds_read_b128 v[168:171], v147 offset:33792
	ds_read_b128 v[192:195], v147 offset:34816
	ds_read_b128 v[196:199], v147 offset:35840
	ds_read_b128 v[200:203], v147 offset:36864
	ds_read_b128 v[204:207], v147 offset:37888
	ds_read_b128 v[208:211], v147 offset:38912
	ds_read_b128 v[212:215], v147 offset:39936
	global_load_lds_dwordx4 v134, s[30:31]
	s_mov_b32 m0, s36
	s_nop 0
	global_load_lds_dwordx4 v132, s[30:31]
	s_waitcnt lgkmcnt(8)
	s_barrier
; #define PG8_STAGE(bufoff, gbase, voff) do { _Pragma("unroll") for (int _i = 0; _i < 2; ++_i) \
;         __builtin_amdgcn_global_load_lds((const unsigned*)((const char*)(gbase) + (voff)[_i]), (LAS unsigned*)(lds + (bufoff) + ldsw + _i * 8192), 16, 0, 0); } while (0)
; #define PG8_LDA(dst, b, h) do { _Pragma("unroll") for (int m = 0; m < 4; ++m) _Pragma("unroll") for (int k = 0; k < 2; ++k) dst[m][k] = *(const LAS bf16x8*)(lds + PG8_SA(b, h) + aoff + m * 2048 + k * 1024); } while (0)
; #define PG8_LDB(dst, b, h) do { _Pragma("unroll") for (int n = 0; n < 2; ++n) _Pragma("unroll") for (int k = 0; k < 2; ++k) dst[n][k] = *(const LAS bf16x8*)(lds + PG8_SB(b, h) + boff + n * 2048 + k * 1024); } while (0)
; #define PG8_MMA(ai, bj, At, Bt_) do { __builtin_amdgcn_s_setprio(1); _Pragma("unroll") for (int m = 0; m < 4; ++m) _Pragma("unroll") for (int n = 0; n < 2; ++n) _Pragma("unroll") for (int k = 0; k < 2; ++k) \
;         acc[ai][bj][m][n] = __builtin_amdgcn_mfma_f32_16x16x32_bf16(Bt_[n][k], At[m][k], acc[ai][bj][m][n], 0, 0, 0); __builtin_amdgcn_s_setprio(0); } while (0)
; #define PG8_WAIT_V(n) asm volatile("s_waitcnt vmcnt(" #n ")" ::: "memory")
; #define PG8_WAIT_L(n) asm volatile("s_waitcnt lgkmcnt(" #n ")" ::: "memory")
; #define PG8_BAR __builtin_amdgcn_s_barrier()
; #define PG8_SCHED __builtin_amdgcn_sched_barrier(0)
; template <bool REMAP>
; DI void gemm_phase(LAS unsigned char* lds, const u16* A, int lda, const u16* Bt, int K, u16* O, int ldc, int nunits) {
;     ...
;             PG8_WAIT_L(8); PG8_BAR; PG8_WAIT_L(0); PG8_MMA(0, 0, At, B0); PG8_BAR; PG8_SCHED;
;             PG8_LDB(B1, 1, 1); PG8_STAGE(PG8_SB(1, 0), b3, voffB);
;             PG8_BAR; PG8_WAIT_L(0); PG8_MMA(0, 1, At, B1); PG8_BAR;
;             PG8_LDA(At, 1, 1); PG8_STAGE(PG8_SA(1, 0), a3, voffA);
;             PG8_BAR; PG8_WAIT_L(0); PG8_MMA(1, 0, At, B0); PG8_BAR; PG8_SCHED;
;             PG8_STAGE(PG8_SB(1, 1), b3 + hstepB, voffB);
;             PG8_WAIT_V(6); PG8_BAR; PG8_MMA(1, 1, At, B1); PG8_BAR;
	s_waitcnt lgkmcnt(0)
	s_waitcnt lgkmcnt(0)
	v_mfma_f32_16x16x32_bf16 v[126:129], v[148:151], v[164:167], v[126:129]
	v_mfma_f32_16x16x32_bf16 v[122:125], v[156:159], v[164:167], v[122:125]
	v_mfma_f32_16x16x32_bf16 v[118:121], v[148:151], v[192:195], v[118:121]
	v_mfma_f32_16x16x32_bf16 v[114:117], v[156:159], v[192:195], v[114:117]
	v_mfma_f32_16x16x32_bf16 v[102:105], v[148:151], v[200:203], v[102:105]
	v_mfma_f32_16x16x32_bf16 v[98:101], v[156:159], v[200:203], v[98:101]
	v_mfma_f32_16x16x32_bf16 v[86:89], v[148:151], v[208:211], v[86:89]
	v_mfma_f32_16x16x32_bf16 v[82:85], v[156:159], v[208:211], v[82:85]
	v_mfma_f32_16x16x32_bf16 v[126:129], v[152:155], v[168:171], v[126:129]
	v_mfma_f32_16x16x32_bf16 v[122:125], v[160:163], v[168:171], v[122:125]
	v_mfma_f32_16x16x32_bf16 v[118:121], v[152:155], v[196:199], v[118:121]
	v_mfma_f32_16x16x32_bf16 v[114:117], v[160:163], v[196:199], v[114:117]
	v_mfma_f32_16x16x32_bf16 v[102:105], v[152:155], v[204:207], v[102:105]
	v_mfma_f32_16x16x32_bf16 v[98:101], v[160:163], v[204:207], v[98:101]
	v_mfma_f32_16x16x32_bf16 v[86:89], v[152:155], v[212:215], v[86:89]
	v_mfma_f32_16x16x32_bf16 v[82:85], v[160:163], v[212:215], v[82:85]
	s_barrier
	s_add_i32 s30, 0, 0x1c000
	s_add_i32 s31, s56, s26
	v_add_u32_e32 v228, s30, v145
	v_lshl_add_u64 v[172:173], v[172:173], 0, s[18:19]
	s_mov_b32 m0, s31
	ds_read_b128 v[216:219], v228
	ds_read_b128 v[220:223], v228 offset:1024
	ds_read_b128 v[224:227], v228 offset:2048
	ds_read_b128 v[228:231], v228 offset:3072
	global_load_lds_dwordx4 v[172:173], off
	v_lshl_add_u64 v[172:173], v[232:233], 0, s[18:19]
	s_add_i32 m0, s31, 0x2000
	s_nop 0
	global_load_lds_dwordx4 v[172:173], off
	s_barrier
	s_waitcnt lgkmcnt(0)
	s_waitcnt lgkmcnt(0)
	v_mfma_f32_16x16x32_bf16 v[110:113], v[216:219], v[164:167], v[110:113]
	v_mfma_f32_16x16x32_bf16 v[106:109], v[224:227], v[164:167], v[106:109]
	v_mfma_f32_16x16x32_bf16 v[94:97], v[216:219], v[192:195], v[94:97]
	v_mfma_f32_16x16x32_bf16 v[90:93], v[224:227], v[192:195], v[90:93]
	v_mfma_f32_16x16x32_bf16 v[78:81], v[216:219], v[200:203], v[78:81]
	v_mfma_f32_16x16x32_bf16 v[74:77], v[224:227], v[200:203], v[74:77]
	v_mfma_f32_16x16x32_bf16 v[70:73], v[216:219], v[208:211], v[70:73]
	v_mfma_f32_16x16x32_bf16 v[66:69], v[224:227], v[208:211], v[66:69]
	v_mfma_f32_16x16x32_bf16 v[110:113], v[220:223], v[168:171], v[110:113]
	v_mfma_f32_16x16x32_bf16 v[106:109], v[228:231], v[168:171], v[106:109]
	v_mfma_f32_16x16x32_bf16 v[94:97], v[220:223], v[196:199], v[94:97]
	v_mfma_f32_16x16x32_bf16 v[90:93], v[228:231], v[196:199], v[90:93]
	v_mfma_f32_16x16x32_bf16 v[78:81], v[220:223], v[204:207], v[78:81]
	v_mfma_f32_16x16x32_bf16 v[74:77], v[228:231], v[204:207], v[74:77]
	v_mfma_f32_16x16x32_bf16 v[70:73], v[220:223], v[212:215], v[70:73]
	v_mfma_f32_16x16x32_bf16 v[66:69], v[228:231], v[212:215], v[66:69]
	s_mov_b32 m0, s37
	s_barrier
	ds_read_b128 v[164:167], v147 offset:49152
	ds_read_b128 v[168:171], v147 offset:50176
	ds_read_b128 v[192:195], v147 offset:51200
	ds_read_b128 v[196:199], v147 offset:52224
	ds_read_b128 v[200:203], v147 offset:53248
	ds_read_b128 v[204:207], v147 offset:54272
	ds_read_b128 v[208:211], v147 offset:55296
	ds_read_b128 v[212:215], v147 offset:56320
	global_load_lds_dwordx4 v134, s[28:29]
	s_mov_b32 m0, s38
	s_nop 0
	global_load_lds_dwordx4 v132, s[28:29]
	s_barrier
	s_waitcnt lgkmcnt(0)
	s_waitcnt lgkmcnt(0)
	v_mfma_f32_16x16x32_bf16 v[62:65], v[148:151], v[164:167], v[62:65]
	v_mfma_f32_16x16x32_bf16 v[58:61], v[156:159], v[164:167], v[58:61]
	v_mfma_f32_16x16x32_bf16 v[54:57], v[148:151], v[192:195], v[54:57]
	v_mfma_f32_16x16x32_bf16 v[50:53], v[156:159], v[192:195], v[50:53]
	v_mfma_f32_16x16x32_bf16 v[38:41], v[148:151], v[200:203], v[38:41]
	v_mfma_f32_16x16x32_bf16 v[34:37], v[156:159], v[200:203], v[34:37]
	v_mfma_f32_16x16x32_bf16 v[22:25], v[148:151], v[208:211], v[22:25]
	v_mfma_f32_16x16x32_bf16 v[18:21], v[156:159], v[208:211], v[18:21]
	v_mfma_f32_16x16x32_bf16 v[62:65], v[152:155], v[168:171], v[62:65]
	v_mfma_f32_16x16x32_bf16 v[58:61], v[160:163], v[168:171], v[58:61]
	v_mfma_f32_16x16x32_bf16 v[54:57], v[152:155], v[196:199], v[54:57]
	v_mfma_f32_16x16x32_bf16 v[50:53], v[160:163], v[196:199], v[50:53]
	v_mfma_f32_16x16x32_bf16 v[38:41], v[152:155], v[204:207], v[38:41]
	v_mfma_f32_16x16x32_bf16 v[34:37], v[160:163], v[204:207], v[34:37]
	v_mfma_f32_16x16x32_bf16 v[22:25], v[152:155], v[212:215], v[22:25]
	v_mfma_f32_16x16x32_bf16 v[18:21], v[160:163], v[212:215], v[18:21]
	s_barrier
	s_add_u32 s22, s22, 0x40080
	s_addc_u32 s23, s23, 0
	s_add_i32 s28, s30, s26
	s_mov_b32 m0, s28
	s_nop 0
	global_load_lds_dwordx4 v0, s[22:23]
	s_add_i32 m0, s28, 0x2000
	s_nop 0
	global_load_lds_dwordx4 v130, s[22:23]
	s_waitcnt vmcnt(6)
	s_barrier
; DI unsigned pk2(float lo, float hi) { fl2_t f = {lo, hi}; bf2_t b = __builtin_convertvector(f, bf2_t); return __builtin_bit_cast(unsigned, b); }
; #define PG8_MMA(ai, bj, At, Bt_) do { __builtin_amdgcn_s_setprio(1); _Pragma("unroll") for (int m = 0; m < 4; ++m) _Pragma("unroll") for (int n = 0; n < 2; ++n) _Pragma("unroll") for (int k = 0; k < 2; ++k) \
;         acc[ai][bj][m][n] = __builtin_amdgcn_mfma_f32_16x16x32_bf16(Bt_[n][k], At[m][k], acc[ai][bj][m][n], 0, 0, 0); __builtin_amdgcn_s_setprio(0); } while (0)
; #define PG8_WAIT_V(n) asm volatile("s_waitcnt vmcnt(" #n ")" ::: "memory")
; #define PG8_BAR __builtin_amdgcn_s_barrier()
; template <bool REMAP>
; DI void gemm_phase(LAS unsigned char* lds, const u16* A, int lda, const u16* Bt, int K, u16* O, int ldc, int nunits) {
;     ...
;             PG8_WAIT_V(6); PG8_BAR; PG8_MMA(1, 1, At, B1); PG8_BAR;
;         }
;         {
;             const int row0 = cur.pm * BM + wr * 64 + fr, col0 = cur.pn * BM + wc * 32 + 8 * fq;
; #pragma unroll
;             for (int ai = 0; ai < 2; ++ai)
; #pragma unroll
;                 for (int m = 0; m < 4; ++m) { u16* rowp = O + (size_t)(row0 + ai * HALF + m * 16) * ldc + col0;
; #pragma unroll
;                     for (int bj = 0; bj < 2; ++bj) { const f32x4 v0 = acc[ai][bj][m][0], v1 = acc[ai][bj][m][1];
;                         u32x4 w = {pk2(v0[0], v0[1]), pk2(v0[2], v0[3]), pk2(v1[0], v1[1]), pk2(v1[2], v1[3])};
;                         *(u32x4*)(rowp + bj * HALF) = w; } }
;         }
;         if (!has_next) break;
; #pragma unroll
;         for (int a = 0; a < 2; ++a)
; #pragma unroll
;             for (int b = 0; b < 2; ++b)
; #pragma unroll
;                 for (int m = 0; m < 4; ++m)
; #pragma unroll
;                     for (int n = 0; n < 2; ++n) acc[a][b][m][n] = (f32x4){0.f, 0.f, 0.f, 0.f};
;         cur = nxt; cA = nA; cB = nB; ++ui;
;     }
;     PG8_WAIT_V(0);
;     if (wr == 0) PG8_BAR;
	v_mfma_f32_16x16x32_bf16 v[46:49], v[216:219], v[164:167], v[46:49]
	v_mfma_f32_16x16x32_bf16 v[42:45], v[224:227], v[164:167], v[42:45]
	v_mfma_f32_16x16x32_bf16 v[30:33], v[216:219], v[192:195], v[30:33]
	v_mfma_f32_16x16x32_bf16 v[26:29], v[224:227], v[192:195], v[26:29]
	v_mfma_f32_16x16x32_bf16 v[14:17], v[216:219], v[200:203], v[14:17]
	v_mfma_f32_16x16x32_bf16 v[10:13], v[224:227], v[200:203], v[10:13]
	v_mfma_f32_16x16x32_bf16 v[6:9], v[216:219], v[208:211], v[6:9]
	v_mfma_f32_16x16x32_bf16 v[2:5], v[224:227], v[208:211], v[2:5]
	v_mfma_f32_16x16x32_bf16 v[46:49], v[220:223], v[168:171], v[46:49]
	v_mfma_f32_16x16x32_bf16 v[42:45], v[228:231], v[168:171], v[42:45]
	v_mfma_f32_16x16x32_bf16 v[30:33], v[220:223], v[196:199], v[30:33]
	v_mfma_f32_16x16x32_bf16 v[26:29], v[228:231], v[196:199], v[26:29]
	v_mfma_f32_16x16x32_bf16 v[14:17], v[220:223], v[204:207], v[14:17]
	v_mfma_f32_16x16x32_bf16 v[10:13], v[228:231], v[204:207], v[10:13]
	v_mfma_f32_16x16x32_bf16 v[6:9], v[220:223], v[212:215], v[6:9]
	v_mfma_f32_16x16x32_bf16 v[2:5], v[228:231], v[212:215], v[2:5]
	s_add_i32 s55, s55, 2
	s_add_u32 s20, s20, 0x100
	s_addc_u32 s21, s21, 0
	s_cmp_gt_u32 s55, 13
	s_barrier
	s_cbranch_scc0 .LBB0_137
	v_lshl_or_b32 v140, s40, 8, v146
	v_lshl_add_u32 v148, s41, 8, v144
	v_ashrrev_i32_e32 v141, 31, v140
	v_lshl_add_u64 v[140:141], v[140:141], 1, s[0:1]
	v_cvt_pk_bf16_f32 v70, v70, v71
	v_cvt_pk_bf16_f32 v71, v72, v73
	v_cvt_pk_bf16_f32 v72, v66, v67
	v_add_u32_e32 v66, 0x80, v148
	v_mad_i64_i32 v[142:143], s[10:11], v148, s52, v[140:141]
	v_cvt_pk_bf16_f32 v110, v110, v111
	v_cvt_pk_bf16_f32 v111, v112, v113
	v_cvt_pk_bf16_f32 v112, v106, v107
	v_cvt_pk_bf16_f32 v113, v108, v109
	v_or_b32_e32 v106, 16, v148
	v_mad_i64_i32 v[66:67], s[10:11], v66, s52, v[140:141]
	v_cvt_pk_bf16_f32 v46, v46, v47
	v_cvt_pk_bf16_f32 v47, v48, v49
	v_cvt_pk_bf16_f32 v48, v42, v43
	v_cvt_pk_bf16_f32 v49, v44, v45
	v_add_u32_e32 v42, 0x90, v148
	flat_store_dwordx4 v[142:143], v[110:113] offset:256
	v_cvt_pk_bf16_f32 v94, v94, v95
	v_cvt_pk_bf16_f32 v95, v96, v97
	v_mad_i64_i32 v[110:111], s[10:11], v106, s52, v[140:141]
	v_cvt_pk_bf16_f32 v96, v90, v91
	v_cvt_pk_bf16_f32 v97, v92, v93
	v_or_b32_e32 v90, 32, v148
	flat_store_dwordx4 v[66:67], v[46:49] offset:256
	v_cvt_pk_bf16_f32 v30, v30, v31
	v_cvt_pk_bf16_f32 v31, v32, v33
	v_mad_i64_i32 v[46:47], s[10:11], v42, s52, v[140:141]
	v_cvt_pk_bf16_f32 v32, v26, v27
	v_cvt_pk_bf16_f32 v33, v28, v29
	v_add_u32_e32 v26, 0xa0, v148
	flat_store_dwordx4 v[110:111], v[94:97] offset:256
	v_cvt_pk_bf16_f32 v78, v78, v79
	v_cvt_pk_bf16_f32 v79, v80, v81
	v_mad_i64_i32 v[94:95], s[10:11], v90, s52, v[140:141]
	v_cvt_pk_bf16_f32 v80, v74, v75
	v_cvt_pk_bf16_f32 v81, v76, v77
	v_or_b32_e32 v74, 48, v148
	flat_store_dwordx4 v[46:47], v[30:33] offset:256
	v_cvt_pk_bf16_f32 v14, v14, v15
	v_cvt_pk_bf16_f32 v15, v16, v17
	v_mad_i64_i32 v[30:31], s[10:11], v26, s52, v[140:141]
	v_cvt_pk_bf16_f32 v16, v10, v11
	v_cvt_pk_bf16_f32 v17, v12, v13
	v_add_u32_e32 v10, 0xb0, v148
	flat_store_dwordx4 v[94:95], v[78:81] offset:256
	flat_store_dwordx4 v[30:31], v[14:17] offset:256
	v_cvt_pk_bf16_f32 v126, v126, v127
	v_mad_i64_i32 v[78:79], s[10:11], v74, s52, v[140:141]
	v_mad_i64_i32 v[14:15], s[10:11], v10, s52, v[140:141]
	v_cvt_pk_bf16_f32 v127, v128, v129
	v_cvt_pk_bf16_f32 v128, v122, v123
	v_cvt_pk_bf16_f32 v129, v124, v125
	v_cvt_pk_bf16_f32 v106, v118, v119
	v_cvt_pk_bf16_f32 v107, v120, v121
	v_cvt_pk_bf16_f32 v108, v114, v115
	v_cvt_pk_bf16_f32 v109, v116, v117
	v_cvt_pk_bf16_f32 v90, v102, v103
	v_cvt_pk_bf16_f32 v91, v104, v105
	v_cvt_pk_bf16_f32 v92, v98, v99
	v_cvt_pk_bf16_f32 v93, v100, v101
	v_cvt_pk_bf16_f32 v74, v86, v87
	v_cvt_pk_bf16_f32 v75, v88, v89
	v_cvt_pk_bf16_f32 v76, v82, v83
	v_cvt_pk_bf16_f32 v77, v84, v85
	v_cvt_pk_bf16_f32 v73, v68, v69
	v_cvt_pk_bf16_f32 v62, v62, v63
	v_cvt_pk_bf16_f32 v63, v64, v65
	v_cvt_pk_bf16_f32 v64, v58, v59
	v_cvt_pk_bf16_f32 v65, v60, v61
	v_cvt_pk_bf16_f32 v42, v54, v55
	v_cvt_pk_bf16_f32 v43, v56, v57
	v_cvt_pk_bf16_f32 v44, v50, v51
	v_cvt_pk_bf16_f32 v45, v52, v53
	v_cvt_pk_bf16_f32 v26, v38, v39
	v_cvt_pk_bf16_f32 v27, v40, v41
	v_cvt_pk_bf16_f32 v28, v34, v35
	v_cvt_pk_bf16_f32 v29, v36, v37
	v_cvt_pk_bf16_f32 v10, v22, v23
	v_cvt_pk_bf16_f32 v11, v24, v25
	v_cvt_pk_bf16_f32 v12, v18, v19
	v_cvt_pk_bf16_f32 v13, v20, v21
	v_cvt_pk_bf16_f32 v6, v6, v7
	v_cvt_pk_bf16_f32 v7, v8, v9
	v_cvt_pk_bf16_f32 v8, v2, v3
	v_cvt_pk_bf16_f32 v9, v4, v5
	s_and_b64 vcc, exec, s[8:9]
	s_mov_b32 s40, s6
	s_mov_b32 s41, s4
	s_mov_b64 s[20:21], s[14:15]
	s_mov_b64 s[10:11], s[12:13]
	flat_store_dwordx4 v[142:143], v[126:129]
	flat_store_dwordx4 v[110:111], v[106:109]
	flat_store_dwordx4 v[94:95], v[90:93]
	flat_store_dwordx4 v[78:79], v[74:77]
	flat_store_dwordx4 v[78:79], v[70:73] offset:256
	flat_store_dwordx4 v[66:67], v[62:65]
	flat_store_dwordx4 v[46:47], v[42:45]
	flat_store_dwordx4 v[30:31], v[26:29]
	flat_store_dwordx4 v[14:15], v[10:13]
	flat_store_dwordx4 v[14:15], v[6:9] offset:256
	s_cbranch_vccz .LBB0_134
	s_waitcnt vmcnt(0)
	s_cmpk_gt_u32 s2, 0xff
	s_cbranch_scc1 .LBB0_141
	s_barrier

; #define PG8_STAGE(bufoff, gbase, voff) do { _Pragma("unroll") for (int _i = 0; _i < 2; ++_i) \
;         __builtin_amdgcn_global_load_lds((const unsigned*)((const char*)(gbase) + (voff)[_i]), (LAS unsigned*)(lds + (bufoff) + ldsw + _i * 8192), 16, 0, 0); } while (0)
; #define PG8_LDA(dst, b, h) do { _Pragma("unroll") for (int m = 0; m < 4; ++m) _Pragma("unroll") for (int k = 0; k < 2; ++k) dst[m][k] = *(const LAS bf16x8*)(lds + PG8_SA(b, h) + aoff + m * 2048 + k * 1024); } while (0)
; #define PG8_LDB(dst, b, h) do { _Pragma("unroll") for (int n = 0; n < 2; ++n) _Pragma("unroll") for (int k = 0; k < 2; ++k) dst[n][k] = *(const LAS bf16x8*)(lds + PG8_SB(b, h) + boff + n * 2048 + k * 1024); } while (0)
; #define PG8_MMA(ai, bj, At, Bt_) do { __builtin_amdgcn_s_setprio(1); _Pragma("unroll") for (int m = 0; m < 4; ++m) _Pragma("unroll") for (int n = 0; n < 2; ++n) _Pragma("unroll") for (int k = 0; k < 2; ++k) \
;         acc[ai][bj][m][n] = __builtin_amdgcn_mfma_f32_16x16x32_bf16(Bt_[n][k], At[m][k], acc[ai][bj][m][n], 0, 0, 0); __builtin_amdgcn_s_setprio(0); } while (0)
; #define PG8_WAIT_L(n) asm volatile("s_waitcnt lgkmcnt(" #n ")" ::: "memory")
; #define PG8_BAR __builtin_amdgcn_s_barrier()
; #define PG8_SCHED __builtin_amdgcn_sched_barrier(0)
; template <bool REMAP>
; DI void gemm_phase(LAS unsigned char* lds, const u16* A, int lda, const u16* Bt, int K, u16* O, int ldc, int nunits) {
;     ...
;     auto akb = [&](int kt) -> size_t { const int k0 = kt * BK; return (size_t)(REMAP ? (k0 < 768 ? k0 : (k0 < 1536 ? k0 + 384 : k0 + 1920)) : k0) * 2; };
;     ...
;         for (int t = 0; t < nt; t += 2) {
;             const bool last = (t == nt - 2);
;             const char* a1 = cA + akb(t + 1);
;             const char* a2 = last ? nA + akb(0) : cA + akb(t + 2); const char* b2 = last ? nB : cB + (size_t)(t + 2) * kstep;
;             const char* a3 = last ? nA + akb(1) : cA + akb(t + 3); const char* b3 = b2 + kstep;
;             PG8_LDB(B0, 0, 0); PG8_SCHED; PG8_LDA(At, 0, 0); PG8_STAGE(PG8_SA(1, 1), a1 + hstepA, voffA);
;             PG8_WAIT_L(8); PG8_BAR; PG8_WAIT_L(0); PG8_MMA(0, 0, At, B0); PG8_BAR; PG8_SCHED;
;             PG8_LDB(B1, 0, 1); PG8_STAGE(PG8_SB(0, 0), b2, voffB);
;             PG8_BAR; PG8_WAIT_L(0); PG8_MMA(0, 1, At, B1); PG8_BAR;
.LBB0_387:
	s_and_b64 s[20:21], exec, s[20:21]
	s_cselect_b32 s21, s5, s47
	s_cselect_b32 s20, s41, s46
	s_cmp_lt_u32 s50, 24
	s_cselect_b32 s51, 0x180, s68
	s_cmp_gt_u32 s50, 11
	s_cselect_b32 s51, s51, 0
	s_add_i32 s51, s51, s49
	s_lshl_b32 s51, s51, 1
	s_addk_i32 s51, 0xff00
	s_add_u32 s51, s6, s51
	s_addc_u32 s55, s7, 0
	s_add_i32 s56, 0, 0x10000
	v_add_u32_e32 v152, s56, v137
	ds_read_b128 v[140:143], v152
	ds_read_b128 v[144:147], v152 offset:1024
	ds_read_b128 v[148:151], v152 offset:2048
	ds_read_b128 v[152:155], v152 offset:3072
	s_add_u32 s54, s51, 0x1c0000
	s_addc_u32 s55, s55, 0
	s_add_i32 m0, s27, 0xc000
	ds_read_b128 v[156:159], v139
	ds_read_b128 v[160:163], v139 offset:1024
	ds_read_b128 v[164:167], v139 offset:2048
	ds_read_b128 v[168:171], v139 offset:3072
	ds_read_b128 v[192:195], v139 offset:4096
	ds_read_b128 v[196:199], v139 offset:5120
	ds_read_b128 v[200:203], v139 offset:6144
	ds_read_b128 v[204:207], v139 offset:7168
	global_load_lds_dwordx4 v134, s[54:55]
	s_add_i32 m0, s27, 0xe000
	s_nop 0
	global_load_lds_dwordx4 v132, s[54:55]
	s_waitcnt lgkmcnt(8)
	s_barrier
	s_waitcnt lgkmcnt(0)
	s_waitcnt lgkmcnt(0)
	v_mfma_f32_16x16x32_bf16 v[126:129], v[140:143], v[156:159], v[126:129]
	v_mfma_f32_16x16x32_bf16 v[122:125], v[148:151], v[156:159], v[122:125]
	v_mfma_f32_16x16x32_bf16 v[118:121], v[140:143], v[164:167], v[118:121]
	v_mfma_f32_16x16x32_bf16 v[114:117], v[148:151], v[164:167], v[114:117]
	v_mfma_f32_16x16x32_bf16 v[102:105], v[140:143], v[192:195], v[102:105]
	v_mfma_f32_16x16x32_bf16 v[98:101], v[148:151], v[192:195], v[98:101]
	v_mfma_f32_16x16x32_bf16 v[86:89], v[140:143], v[200:203], v[86:89]
	v_mfma_f32_16x16x32_bf16 v[82:85], v[148:151], v[200:203], v[82:85]
	v_mfma_f32_16x16x32_bf16 v[126:129], v[144:147], v[160:163], v[126:129]
	v_mfma_f32_16x16x32_bf16 v[122:125], v[152:155], v[160:163], v[122:125]
	v_mfma_f32_16x16x32_bf16 v[118:121], v[144:147], v[168:171], v[118:121]
	v_mfma_f32_16x16x32_bf16 v[114:117], v[152:155], v[168:171], v[114:117]
	v_mfma_f32_16x16x32_bf16 v[102:105], v[144:147], v[196:199], v[102:105]
	v_mfma_f32_16x16x32_bf16 v[98:101], v[152:155], v[196:199], v[98:101]
	v_mfma_f32_16x16x32_bf16 v[86:89], v[144:147], v[204:207], v[86:89]
	v_mfma_f32_16x16x32_bf16 v[82:85], v[152:155], v[204:207], v[82:85]
	s_barrier
	s_add_i32 s51, 0, 0x14000
	v_add_u32_e32 v172, s51, v137
	s_add_i32 s54, s56, s26
	ds_read_b128 v[208:211], v172
	ds_read_b128 v[212:215], v172 offset:1024
	ds_read_b128 v[216:219], v172 offset:2048
	ds_read_b128 v[220:223], v172 offset:3072
	v_lshl_add_u64 v[172:173], s[20:21], 0, v[0:1]
	s_mov_b32 m0, s54
	v_lshl_add_u64 v[224:225], s[20:21], 0, v[130:131]
	global_load_lds_dwordx4 v[172:173], off
	s_add_i32 m0, s54, 0x2000
	s_nop 0
	global_load_lds_dwordx4 v[224:225], off
	s_barrier
	s_waitcnt lgkmcnt(0)
	s_waitcnt lgkmcnt(0)
	v_mfma_f32_16x16x32_bf16 v[110:113], v[208:211], v[156:159], v[110:113]
	v_mfma_f32_16x16x32_bf16 v[106:109], v[216:219], v[156:159], v[106:109]
	v_mfma_f32_16x16x32_bf16 v[94:97], v[208:211], v[164:167], v[94:97]
	v_mfma_f32_16x16x32_bf16 v[90:93], v[216:219], v[164:167], v[90:93]
	v_mfma_f32_16x16x32_bf16 v[78:81], v[208:211], v[192:195], v[78:81]
	v_mfma_f32_16x16x32_bf16 v[74:77], v[216:219], v[192:195], v[74:77]
	v_mfma_f32_16x16x32_bf16 v[70:73], v[208:211], v[200:203], v[70:73]
	v_mfma_f32_16x16x32_bf16 v[66:69], v[216:219], v[200:203], v[66:69]
	v_mfma_f32_16x16x32_bf16 v[110:113], v[212:215], v[160:163], v[110:113]
	v_mfma_f32_16x16x32_bf16 v[106:109], v[220:223], v[160:163], v[106:109]
	v_mfma_f32_16x16x32_bf16 v[94:97], v[212:215], v[168:171], v[94:97]
	v_mfma_f32_16x16x32_bf16 v[90:93], v[220:223], v[168:171], v[90:93]
	v_mfma_f32_16x16x32_bf16 v[78:81], v[212:215], v[196:199], v[78:81]
	v_mfma_f32_16x16x32_bf16 v[74:77], v[220:223], v[196:199], v[74:77]
	v_mfma_f32_16x16x32_bf16 v[70:73], v[212:215], v[204:207], v[70:73]
	v_mfma_f32_16x16x32_bf16 v[66:69], v[220:223], v[204:207], v[66:69]
	s_mov_b32 m0, s27
	s_barrier
	ds_read_b128 v[156:159], v139 offset:16384
	ds_read_b128 v[160:163], v139 offset:17408
	ds_read_b128 v[164:167], v139 offset:18432
	ds_read_b128 v[168:171], v139 offset:19456
	ds_read_b128 v[192:195], v139 offset:20480
	ds_read_b128 v[196:199], v139 offset:21504
	ds_read_b128 v[200:203], v139 offset:22528
	ds_read_b128 v[204:207], v139 offset:23552
	global_load_lds_dwordx4 v134, s[28:29]
	s_mov_b32 m0, s30
	s_nop 0
	global_load_lds_dwordx4 v132, s[28:29]
	s_barrier
	s_waitcnt lgkmcnt(0)
	s_waitcnt lgkmcnt(0)
	v_mfma_f32_16x16x32_bf16 v[62:65], v[140:143], v[156:159], v[62:65]
	v_mfma_f32_16x16x32_bf16 v[58:61], v[148:151], v[156:159], v[58:61]
	v_mfma_f32_16x16x32_bf16 v[54:57], v[140:143], v[164:167], v[54:57]
	v_mfma_f32_16x16x32_bf16 v[50:53], v[148:151], v[164:167], v[50:53]
	v_mfma_f32_16x16x32_bf16 v[38:41], v[140:143], v[192:195], v[38:41]
	v_mfma_f32_16x16x32_bf16 v[34:37], v[148:151], v[192:195], v[34:37]
	v_mfma_f32_16x16x32_bf16 v[22:25], v[140:143], v[200:203], v[22:25]
	v_mfma_f32_16x16x32_bf16 v[18:21], v[148:151], v[200:203], v[18:21]
	v_mfma_f32_16x16x32_bf16 v[62:65], v[144:147], v[160:163], v[62:65]
	v_mfma_f32_16x16x32_bf16 v[58:61], v[152:155], v[160:163], v[58:61]
	v_mfma_f32_16x16x32_bf16 v[54:57], v[144:147], v[168:171], v[54:57]
	v_mfma_f32_16x16x32_bf16 v[50:53], v[152:155], v[168:171], v[50:53]
	v_mfma_f32_16x16x32_bf16 v[38:41], v[144:147], v[196:199], v[38:41]
	v_mfma_f32_16x16x32_bf16 v[34:37], v[152:155], v[196:199], v[34:37]
	v_mfma_f32_16x16x32_bf16 v[22:25], v[144:147], v[204:207], v[22:25]
	v_mfma_f32_16x16x32_bf16 v[18:21], v[152:155], v[204:207], v[18:21]
	s_barrier
; #define PG8_STAGE(bufoff, gbase, voff) do { _Pragma("unroll") for (int _i = 0; _i < 2; ++_i) \
;         __builtin_amdgcn_global_load_lds((const unsigned*)((const char*)(gbase) + (voff)[_i]), (LAS unsigned*)(lds + (bufoff) + ldsw + _i * 8192), 16, 0, 0); } while (0)
; #define PG8_LDA(dst, b, h) do { _Pragma("unroll") for (int m = 0; m < 4; ++m) _Pragma("unroll") for (int k = 0; k < 2; ++k) dst[m][k] = *(const LAS bf16x8*)(lds + PG8_SA(b, h) + aoff + m * 2048 + k * 1024); } while (0)
; #define PG8_LDB(dst, b, h) do { _Pragma("unroll") for (int n = 0; n < 2; ++n) _Pragma("unroll") for (int k = 0; k < 2; ++k) dst[n][k] = *(const LAS bf16x8*)(lds + PG8_SB(b, h) + boff + n * 2048 + k * 1024); } while (0)
; #define PG8_MMA(ai, bj, At, Bt_) do { __builtin_amdgcn_s_setprio(1); _Pragma("unroll") for (int m = 0; m < 4; ++m) _Pragma("unroll") for (int n = 0; n < 2; ++n) _Pragma("unroll") for (int k = 0; k < 2; ++k) \
;         acc[ai][bj][m][n] = __builtin_amdgcn_mfma_f32_16x16x32_bf16(Bt_[n][k], At[m][k], acc[ai][bj][m][n], 0, 0, 0); __builtin_amdgcn_s_setprio(0); } while (0)
; #define PG8_WAIT_V(n) asm volatile("s_waitcnt vmcnt(" #n ")" ::: "memory")
; #define PG8_WAIT_L(n) asm volatile("s_waitcnt lgkmcnt(" #n ")" ::: "memory")
; #define PG8_BAR __builtin_amdgcn_s_barrier()
; #define PG8_SCHED __builtin_amdgcn_sched_barrier(0)
; template <bool REMAP>
; DI void gemm_phase(LAS unsigned char* lds, const u16* A, int lda, const u16* Bt, int K, u16* O, int ldc, int nunits) {
;     ...
;             PG8_BAR; PG8_WAIT_L(0); PG8_MMA(1, 0, At, B0); PG8_BAR; PG8_SCHED;
;             PG8_STAGE(PG8_SB(0, 1), b2 + hstepB, voffB);
;             PG8_WAIT_V(6); PG8_BAR; PG8_MMA(1, 1, At, B1); PG8_BAR;
;             PG8_LDB(B0, 1, 0); PG8_SCHED; PG8_LDA(At, 1, 0); PG8_STAGE(PG8_SA(0, 1), a2 + hstepA, voffA);
;             PG8_WAIT_L(8); PG8_BAR; PG8_WAIT_L(0); PG8_MMA(0, 0, At, B0); PG8_BAR; PG8_SCHED;
;             PG8_LDB(B1, 1, 1); PG8_STAGE(PG8_SB(1, 0), b3, voffB);
	s_add_u32 s54, s20, 0x80000
	s_addc_u32 s55, s21, 0
	s_add_i32 s51, s51, s26
	s_mov_b32 m0, s51
	s_nop 0
	global_load_lds_dwordx4 v0, s[54:55]
	s_add_i32 m0, s51, 0x2000
	s_nop 0
	global_load_lds_dwordx4 v130, s[54:55]
	s_waitcnt vmcnt(6)
	s_barrier
	v_mfma_f32_16x16x32_bf16 v[46:49], v[208:211], v[156:159], v[46:49]
	v_mfma_f32_16x16x32_bf16 v[42:45], v[216:219], v[156:159], v[42:45]
	v_mfma_f32_16x16x32_bf16 v[30:33], v[208:211], v[164:167], v[30:33]
	v_mfma_f32_16x16x32_bf16 v[26:29], v[216:219], v[164:167], v[26:29]
	v_mfma_f32_16x16x32_bf16 v[14:17], v[208:211], v[192:195], v[14:17]
	v_mfma_f32_16x16x32_bf16 v[10:13], v[216:219], v[192:195], v[10:13]
	v_mfma_f32_16x16x32_bf16 v[6:9], v[208:211], v[200:203], v[6:9]
	v_mfma_f32_16x16x32_bf16 v[2:5], v[216:219], v[200:203], v[2:5]
	v_mfma_f32_16x16x32_bf16 v[46:49], v[212:215], v[160:163], v[46:49]
	v_mfma_f32_16x16x32_bf16 v[42:45], v[220:223], v[160:163], v[42:45]
	v_mfma_f32_16x16x32_bf16 v[30:33], v[212:215], v[168:171], v[30:33]
	v_mfma_f32_16x16x32_bf16 v[26:29], v[220:223], v[168:171], v[26:29]
	v_mfma_f32_16x16x32_bf16 v[14:17], v[212:215], v[196:199], v[14:17]
	v_mfma_f32_16x16x32_bf16 v[10:13], v[220:223], v[196:199], v[10:13]
	v_mfma_f32_16x16x32_bf16 v[6:9], v[212:215], v[204:207], v[6:9]
	v_mfma_f32_16x16x32_bf16 v[2:5], v[220:223], v[204:207], v[2:5]
	s_add_i32 s51, 0, 0x18000
	v_add_u32_e32 v152, s51, v137
	s_barrier
	ds_read_b128 v[140:143], v152
	ds_read_b128 v[144:147], v152 offset:1024
	ds_read_b128 v[148:151], v152 offset:2048
	ds_read_b128 v[152:155], v152 offset:3072
	s_add_u32 s28, s28, 0x1c0000
	s_addc_u32 s29, s29, 0
	s_mov_b32 m0, s31
	ds_read_b128 v[156:159], v139 offset:32768
	ds_read_b128 v[160:163], v139 offset:33792
	ds_read_b128 v[164:167], v139 offset:34816
	ds_read_b128 v[168:171], v139 offset:35840
	ds_read_b128 v[192:195], v139 offset:36864
	ds_read_b128 v[196:199], v139 offset:37888
	ds_read_b128 v[200:203], v139 offset:38912
	ds_read_b128 v[204:207], v139 offset:39936
	global_load_lds_dwordx4 v134, s[28:29]
	s_mov_b32 m0, s34
	s_nop 0
	global_load_lds_dwordx4 v132, s[28:29]
	s_waitcnt lgkmcnt(8)
	s_barrier
	s_waitcnt lgkmcnt(0)
	s_waitcnt lgkmcnt(0)
	v_mfma_f32_16x16x32_bf16 v[126:129], v[140:143], v[156:159], v[126:129]
	v_mfma_f32_16x16x32_bf16 v[122:125], v[148:151], v[156:159], v[122:125]
	v_mfma_f32_16x16x32_bf16 v[118:121], v[140:143], v[164:167], v[118:121]
	v_mfma_f32_16x16x32_bf16 v[114:117], v[148:151], v[164:167], v[114:117]
	v_mfma_f32_16x16x32_bf16 v[102:105], v[140:143], v[192:195], v[102:105]
	v_mfma_f32_16x16x32_bf16 v[98:101], v[148:151], v[192:195], v[98:101]
	v_mfma_f32_16x16x32_bf16 v[86:89], v[140:143], v[200:203], v[86:89]
	v_mfma_f32_16x16x32_bf16 v[82:85], v[148:151], v[200:203], v[82:85]
	v_mfma_f32_16x16x32_bf16 v[126:129], v[144:147], v[160:163], v[126:129]
	v_mfma_f32_16x16x32_bf16 v[122:125], v[152:155], v[160:163], v[122:125]
	v_mfma_f32_16x16x32_bf16 v[118:121], v[144:147], v[168:171], v[118:121]
	v_mfma_f32_16x16x32_bf16 v[114:117], v[152:155], v[168:171], v[114:117]
	v_mfma_f32_16x16x32_bf16 v[102:105], v[144:147], v[196:199], v[102:105]
	v_mfma_f32_16x16x32_bf16 v[98:101], v[152:155], v[196:199], v[98:101]
	v_mfma_f32_16x16x32_bf16 v[86:89], v[144:147], v[204:207], v[86:89]
	v_mfma_f32_16x16x32_bf16 v[82:85], v[152:155], v[204:207], v[82:85]
	s_barrier
	s_add_i32 s28, 0, 0x1c000
	s_add_i32 s29, s51, s26
	v_add_u32_e32 v220, s28, v137
	v_lshl_add_u64 v[172:173], v[172:173], 0, s[18:19]
	s_mov_b32 m0, s29
	ds_read_b128 v[208:211], v220
	ds_read_b128 v[212:215], v220 offset:1024
	ds_read_b128 v[216:219], v220 offset:2048
	ds_read_b128 v[220:223], v220 offset:3072
	global_load_lds_dwordx4 v[172:173], off
	v_lshl_add_u64 v[172:173], v[224:225], 0, s[18:19]
	s_add_i32 m0, s29, 0x2000
	s_nop 0
	global_load_lds_dwordx4 v[172:173], off
	s_barrier
; #define PG8_STAGE(bufoff, gbase, voff) do { _Pragma("unroll") for (int _i = 0; _i < 2; ++_i) \
;         __builtin_amdgcn_global_load_lds((const unsigned*)((const char*)(gbase) + (voff)[_i]), (LAS unsigned*)(lds + (bufoff) + ldsw + _i * 8192), 16, 0, 0); } while (0)
; #define PG8_LDA(dst, b, h) do { _Pragma("unroll") for (int m = 0; m < 4; ++m) _Pragma("unroll") for (int k = 0; k < 2; ++k) dst[m][k] = *(const LAS bf16x8*)(lds + PG8_SA(b, h) + aoff + m * 2048 + k * 1024); } while (0)
; #define PG8_LDB(dst, b, h) do { _Pragma("unroll") for (int n = 0; n < 2; ++n) _Pragma("unroll") for (int k = 0; k < 2; ++k) dst[n][k] = *(const LAS bf16x8*)(lds + PG8_SB(b, h) + boff + n * 2048 + k * 1024); } while (0)
; #define PG8_MMA(ai, bj, At, Bt_) do { __builtin_amdgcn_s_setprio(1); _Pragma("unroll") for (int m = 0; m < 4; ++m) _Pragma("unroll") for (int n = 0; n < 2; ++n) _Pragma("unroll") for (int k = 0; k < 2; ++k) \
;         acc[ai][bj][m][n] = __builtin_amdgcn_mfma_f32_16x16x32_bf16(Bt_[n][k], At[m][k], acc[ai][bj][m][n], 0, 0, 0); __builtin_amdgcn_s_setprio(0); } while (0)
; #define PG8_WAIT_V(n) asm volatile("s_waitcnt vmcnt(" #n ")" ::: "memory")
; #define PG8_WAIT_L(n) asm volatile("s_waitcnt lgkmcnt(" #n ")" ::: "memory")
; #define PG8_BAR __builtin_amdgcn_s_barrier()
; #define PG8_SCHED __builtin_amdgcn_sched_barrier(0)
; template <bool REMAP>
; DI void gemm_phase(LAS unsigned char* lds, const u16* A, int lda, const u16* Bt, int K, u16* O, int ldc, int nunits) {
;     ...
;             PG8_LDB(B1, 1, 1); PG8_STAGE(PG8_SB(1, 0), b3, voffB);
;             PG8_BAR; PG8_WAIT_L(0); PG8_MMA(0, 1, At, B1); PG8_BAR;
;             PG8_LDA(At, 1, 1); PG8_STAGE(PG8_SA(1, 0), a3, voffA);
;             PG8_BAR; PG8_WAIT_L(0); PG8_MMA(1, 0, At, B0); PG8_BAR; PG8_SCHED;
;             PG8_STAGE(PG8_SB(1, 1), b3 + hstepB, voffB);
;             PG8_WAIT_V(6); PG8_BAR; PG8_MMA(1, 1, At, B1); PG8_BAR;
	s_waitcnt lgkmcnt(0)
	s_waitcnt lgkmcnt(0)
	v_mfma_f32_16x16x32_bf16 v[110:113], v[208:211], v[156:159], v[110:113]
	v_mfma_f32_16x16x32_bf16 v[106:109], v[216:219], v[156:159], v[106:109]
	v_mfma_f32_16x16x32_bf16 v[94:97], v[208:211], v[164:167], v[94:97]
	v_mfma_f32_16x16x32_bf16 v[90:93], v[216:219], v[164:167], v[90:93]
	v_mfma_f32_16x16x32_bf16 v[78:81], v[208:211], v[192:195], v[78:81]
	v_mfma_f32_16x16x32_bf16 v[74:77], v[216:219], v[192:195], v[74:77]
	v_mfma_f32_16x16x32_bf16 v[70:73], v[208:211], v[200:203], v[70:73]
	v_mfma_f32_16x16x32_bf16 v[66:69], v[216:219], v[200:203], v[66:69]
	v_mfma_f32_16x16x32_bf16 v[110:113], v[212:215], v[160:163], v[110:113]
	v_mfma_f32_16x16x32_bf16 v[106:109], v[220:223], v[160:163], v[106:109]
	v_mfma_f32_16x16x32_bf16 v[94:97], v[212:215], v[168:171], v[94:97]
	v_mfma_f32_16x16x32_bf16 v[90:93], v[220:223], v[168:171], v[90:93]
	v_mfma_f32_16x16x32_bf16 v[78:81], v[212:215], v[196:199], v[78:81]
	v_mfma_f32_16x16x32_bf16 v[74:77], v[220:223], v[196:199], v[74:77]
	v_mfma_f32_16x16x32_bf16 v[70:73], v[212:215], v[204:207], v[70:73]
	v_mfma_f32_16x16x32_bf16 v[66:69], v[220:223], v[204:207], v[66:69]
	s_mov_b32 m0, s35
	s_barrier
	ds_read_b128 v[156:159], v139 offset:49152
	ds_read_b128 v[160:163], v139 offset:50176
	ds_read_b128 v[164:167], v139 offset:51200
	ds_read_b128 v[168:171], v139 offset:52224
	ds_read_b128 v[192:195], v139 offset:53248
	ds_read_b128 v[196:199], v139 offset:54272
	ds_read_b128 v[200:203], v139 offset:55296
	ds_read_b128 v[204:207], v139 offset:56320
	global_load_lds_dwordx4 v134, s[22:23]
	s_mov_b32 m0, s36
	s_nop 0
	global_load_lds_dwordx4 v132, s[22:23]
	s_barrier
	s_waitcnt lgkmcnt(0)
	s_waitcnt lgkmcnt(0)
	v_mfma_f32_16x16x32_bf16 v[62:65], v[140:143], v[156:159], v[62:65]
	v_mfma_f32_16x16x32_bf16 v[58:61], v[148:151], v[156:159], v[58:61]
	v_mfma_f32_16x16x32_bf16 v[54:57], v[140:143], v[164:167], v[54:57]
	v_mfma_f32_16x16x32_bf16 v[50:53], v[148:151], v[164:167], v[50:53]
	v_mfma_f32_16x16x32_bf16 v[38:41], v[140:143], v[192:195], v[38:41]
	v_mfma_f32_16x16x32_bf16 v[34:37], v[148:151], v[192:195], v[34:37]
	v_mfma_f32_16x16x32_bf16 v[22:25], v[140:143], v[200:203], v[22:25]
	v_mfma_f32_16x16x32_bf16 v[18:21], v[148:151], v[200:203], v[18:21]
	v_mfma_f32_16x16x32_bf16 v[62:65], v[144:147], v[160:163], v[62:65]
	v_mfma_f32_16x16x32_bf16 v[58:61], v[152:155], v[160:163], v[58:61]
	v_mfma_f32_16x16x32_bf16 v[54:57], v[144:147], v[168:171], v[54:57]
	v_mfma_f32_16x16x32_bf16 v[50:53], v[152:155], v[168:171], v[50:53]
	v_mfma_f32_16x16x32_bf16 v[38:41], v[144:147], v[196:199], v[38:41]
	v_mfma_f32_16x16x32_bf16 v[34:37], v[152:155], v[196:199], v[34:37]
	v_mfma_f32_16x16x32_bf16 v[22:25], v[144:147], v[204:207], v[22:25]
	v_mfma_f32_16x16x32_bf16 v[18:21], v[152:155], v[204:207], v[18:21]
	s_barrier
	s_add_u32 s20, s20, 0x80080
	s_addc_u32 s21, s21, 0
	s_add_i32 s22, s28, s26
	s_mov_b32 m0, s22
	s_nop 0
	global_load_lds_dwordx4 v0, s[20:21]
	s_add_i32 m0, s22, 0x2000
	s_nop 0
	global_load_lds_dwordx4 v130, s[20:21]
	s_waitcnt vmcnt(6)
	s_barrier
	v_mfma_f32_16x16x32_bf16 v[46:49], v[208:211], v[156:159], v[46:49]
	v_mfma_f32_16x16x32_bf16 v[42:45], v[216:219], v[156:159], v[42:45]
	v_mfma_f32_16x16x32_bf16 v[30:33], v[208:211], v[164:167], v[30:33]
	v_mfma_f32_16x16x32_bf16 v[26:29], v[216:219], v[164:167], v[26:29]
	v_mfma_f32_16x16x32_bf16 v[14:17], v[208:211], v[192:195], v[14:17]
	v_mfma_f32_16x16x32_bf16 v[10:13], v[216:219], v[192:195], v[10:13]
	v_mfma_f32_16x16x32_bf16 v[6:9], v[208:211], v[200:203], v[6:9]
	v_mfma_f32_16x16x32_bf16 v[2:5], v[216:219], v[200:203], v[2:5]
	v_mfma_f32_16x16x32_bf16 v[46:49], v[212:215], v[160:163], v[46:49]
	v_mfma_f32_16x16x32_bf16 v[42:45], v[220:223], v[160:163], v[42:45]
	v_mfma_f32_16x16x32_bf16 v[30:33], v[212:215], v[168:171], v[30:33]
	v_mfma_f32_16x16x32_bf16 v[26:29], v[220:223], v[168:171], v[26:29]
	v_mfma_f32_16x16x32_bf16 v[14:17], v[212:215], v[196:199], v[14:17]
	v_mfma_f32_16x16x32_bf16 v[10:13], v[220:223], v[196:199], v[10:13]
	v_mfma_f32_16x16x32_bf16 v[6:9], v[212:215], v[204:207], v[6:9]
	v_mfma_f32_16x16x32_bf16 v[2:5], v[220:223], v[204:207], v[2:5]
	s_add_i32 s20, s50, 2
	s_add_u32 s46, s46, 0x100
	s_addc_u32 s47, s47, 0
	s_addk_i32 s49, 0x80
	s_cmp_gt_u32 s50, 29
	s_mov_b32 s50, s20
	s_barrier
	s_cbranch_scc1 .LBB0_381
